# sgu transposed LDS tile XOR-swizzled (16-byte chunk index ^ (row>>3)&15) on top of the phase-2 wave-group reordering
# speedup vs baseline: 1.0055x; 1.0055x over previous
.LBB0_405:
	s_lshr_b32 s1, s30, 1
	s_and_b32 s0, s30, 7
	s_and_b32 s1, s1, 0x1fffff8
	v_mov_b32_e32 v66, v186
	v_mov_b32_e32 v60, v186
	s_or_b32 s0, s1, s0
	s_lshl_b32 s31, s0, 7
	v_ashrrev_i32_e32 v61, 6, v60
	s_waitcnt lgkmcnt(0)
	v_and_b32_e32 v4, 63, v66
	v_lshl_add_u32 v6, v61, 4, s31
	s_waitcnt lgkmcnt(0)
	v_mov_b64_e32 v[0:1], s[18:19]
	v_mad_i64_i32 v[2:3], s[0:1], v6, s66, v[0:1]
	v_lshlrev_b32_e32 v64, 4, v4
	v_lshl_add_u64 v[2:3], v[2:3], 0, v[64:65]
	v_or_b32_e32 v4, 1, v6
	v_add_co_u32_e32 v2, vcc, s76, v2
	v_mad_i64_i32 v[4:5], s[0:1], v4, s66, v[0:1]
	s_nop 0
	v_addc_co_u32_e32 v3, vcc, 0, v3, vcc
	v_lshl_add_u64 v[4:5], v[4:5], 0, v[64:65]
	v_add_co_u32_e32 v4, vcc, s76, v4
	v_and_b32_e32 v62, 64, v190
	s_nop 0
	v_addc_co_u32_e32 v5, vcc, 0, v5, vcc
	global_load_dwordx4 v[68:71], v[2:3], off offset:2608
	global_load_dwordx4 v[56:59], v[4:5], off offset:2608
	v_or_b32_e32 v2, 2, v6
	v_mad_i64_i32 v[2:3], s[0:1], v2, s66, v[0:1]
	v_lshl_add_u64 v[2:3], v[2:3], 0, v[64:65]
	v_or_b32_e32 v4, 3, v6
	v_add_co_u32_e32 v2, vcc, s76, v2
	v_mad_i64_i32 v[4:5], s[0:1], v4, s66, v[0:1]
	s_nop 0
	v_addc_co_u32_e32 v3, vcc, 0, v3, vcc
	v_lshl_add_u64 v[4:5], v[4:5], 0, v[64:65]
	v_add_co_u32_e32 v4, vcc, s76, v4
	v_add_u32_e32 v62, 64, v62
	s_nop 0
	v_addc_co_u32_e32 v5, vcc, 0, v5, vcc
	global_load_dwordx4 v[52:55], v[2:3], off offset:2608
	global_load_dwordx4 v[48:51], v[4:5], off offset:2608
	v_or_b32_e32 v2, 4, v6
	v_mad_i64_i32 v[2:3], s[0:1], v2, s66, v[0:1]
	v_lshl_add_u64 v[2:3], v[2:3], 0, v[64:65]
	v_or_b32_e32 v4, 5, v6
	v_add_co_u32_e32 v2, vcc, s76, v2
	v_mad_i64_i32 v[4:5], s[0:1], v4, s66, v[0:1]
	s_nop 0
	v_addc_co_u32_e32 v3, vcc, 0, v3, vcc
	v_lshl_add_u64 v[4:5], v[4:5], 0, v[64:65]
	v_add_co_u32_e32 v4, vcc, s76, v4
	v_xor_b32_e32 v63, 1, v190
	s_nop 0
	v_addc_co_u32_e32 v5, vcc, 0, v5, vcc
	global_load_dwordx4 v[44:47], v[2:3], off offset:2608
	global_load_dwordx4 v[40:43], v[4:5], off offset:2608
	v_or_b32_e32 v2, 6, v6
	v_mad_i64_i32 v[2:3], s[0:1], v2, s66, v[0:1]
	v_lshl_add_u64 v[2:3], v[2:3], 0, v[64:65]
	v_or_b32_e32 v4, 7, v6
	v_add_co_u32_e32 v2, vcc, s76, v2
	v_mad_i64_i32 v[4:5], s[0:1], v4, s66, v[0:1]
	s_nop 0
	v_addc_co_u32_e32 v3, vcc, 0, v3, vcc
	v_lshl_add_u64 v[4:5], v[4:5], 0, v[64:65]
	v_add_co_u32_e32 v4, vcc, s76, v4
	s_bfe_u32 s34, s30, 0x10003
	s_nop 0
	v_addc_co_u32_e32 v5, vcc, 0, v5, vcc
	global_load_dwordx4 v[36:39], v[2:3], off offset:2608
	global_load_dwordx4 v[32:35], v[4:5], off offset:2608
	v_or_b32_e32 v2, 8, v6
	v_mad_i64_i32 v[2:3], s[0:1], v2, s66, v[0:1]
	v_lshl_add_u64 v[2:3], v[2:3], 0, v[64:65]
	v_or_b32_e32 v4, 9, v6
	v_add_co_u32_e32 v2, vcc, s76, v2
	v_mad_i64_i32 v[4:5], s[0:1], v4, s66, v[0:1]
	s_nop 0
	v_addc_co_u32_e32 v3, vcc, 0, v3, vcc
	v_lshl_add_u64 v[4:5], v[4:5], 0, v[64:65]
	v_add_co_u32_e32 v4, vcc, s76, v4
	v_lshl_add_u32 v61, v61, 5, 0
	s_nop 0
	v_addc_co_u32_e32 v5, vcc, 0, v5, vcc
	global_load_dwordx4 v[28:31], v[2:3], off offset:2608
	global_load_dwordx4 v[24:27], v[4:5], off offset:2608
	v_or_b32_e32 v2, 10, v6
	v_mad_i64_i32 v[2:3], s[0:1], v2, s66, v[0:1]
	v_lshl_add_u64 v[2:3], v[2:3], 0, v[64:65]
	v_or_b32_e32 v4, 11, v6
	v_add_co_u32_e32 v2, vcc, s76, v2
	v_mad_i64_i32 v[4:5], s[0:1], v4, s66, v[0:1]
	s_nop 0
	v_addc_co_u32_e32 v3, vcc, 0, v3, vcc
	v_lshl_add_u64 v[4:5], v[4:5], 0, v[64:65]
	v_add_co_u32_e32 v4, vcc, s76, v4
	s_waitcnt vmcnt(0)
	v_lshlrev_b32_e32 v72, 16, v70
	v_addc_co_u32_e32 v5, vcc, 0, v5, vcc
	global_load_dwordx4 v[20:23], v[2:3], off offset:2608
	global_load_dwordx4 v[16:19], v[4:5], off offset:2608
	v_or_b32_e32 v2, 12, v6
	v_mad_i64_i32 v[2:3], s[0:1], v2, s66, v[0:1]
	v_lshl_add_u64 v[2:3], v[2:3], 0, v[64:65]
	v_or_b32_e32 v4, 13, v6
	v_add_co_u32_e32 v2, vcc, s76, v2
	v_mad_i64_i32 v[4:5], s[0:1], v4, s66, v[0:1]
	s_nop 0
	v_addc_co_u32_e32 v3, vcc, 0, v3, vcc
	v_lshl_add_u64 v[4:5], v[4:5], 0, v[64:65]
	v_add_co_u32_e32 v4, vcc, s76, v4
	v_and_b32_e32 v70, 0xffff0000, v70
	s_nop 0
	v_addc_co_u32_e32 v5, vcc, 0, v5, vcc
	global_load_dwordx4 v[12:15], v[2:3], off offset:2608
	global_load_dwordx4 v[8:11], v[4:5], off offset:2608
	v_or_b32_e32 v2, 14, v6
	v_mad_i64_i32 v[2:3], s[0:1], v2, s66, v[0:1]
	v_lshl_add_u64 v[2:3], v[2:3], 0, v[64:65]
	v_or_b32_e32 v4, 15, v6
	v_add_co_u32_e32 v2, vcc, s76, v2
	v_mad_i64_i32 v[0:1], s[0:1], v4, s66, v[0:1]
	s_nop 0
	v_addc_co_u32_e32 v3, vcc, 0, v3, vcc
	v_lshl_add_u64 v[0:1], v[0:1], 0, v[64:65]
	v_add_co_u32_e32 v0, vcc, s76, v0
	v_and_b32_e32 v64, 0xffff0000, v68
	s_nop 0
	v_addc_co_u32_e32 v1, vcc, 0, v1, vcc
	v_cmp_lt_i32_e32 vcc, v63, v62
	v_lshlrev_b32_e32 v75, 16, v71
	v_and_b32_e32 v71, 0xffff0000, v71
	v_cndmask_b32_e32 v63, v190, v63, vcc
	v_lshlrev_b32_e32 v144, 2, v63
	v_lshlrev_b32_e32 v63, 16, v68
	v_mul_f32_e32 v67, 0x3d372713, v63
	v_mul_f32_e32 v67, v67, v63
	v_fma_f32 v67, v67, v63, v63
	v_mul_f32_e32 v67, 0x3f4c422a, v67
	v_add_f32_e32 v67, v67, v67
	v_mul_f32_e32 v67, 0x3fb8aa3b, v67
	v_exp_f32_e32 v67, v67
	v_lshlrev_b32_e32 v68, 16, v69
	v_and_b32_e32 v69, 0xffff0000, v69
	v_mul_f32_e32 v63, 0.5, v63
	v_add_f32_e32 v67, 1.0, v67
	v_div_scale_f32 v73, s[0:1], v67, v67, 2.0
	v_rcp_f32_e32 v74, v73
	global_load_dwordx4 v[4:7], v[2:3], off offset:2608
	s_nop 0
	global_load_dwordx4 v[0:3], v[0:1], off offset:2608
	v_fma_f32 v76, -v73, v74, 1.0
	v_fmac_f32_e32 v74, v76, v74
	v_div_scale_f32 v76, vcc, 2.0, v67, 2.0
	v_mul_f32_e32 v77, v76, v74
	v_fma_f32 v78, -v73, v77, v76
	v_fmac_f32_e32 v77, v78, v74
	v_fma_f32 v73, -v73, v77, v76
	v_mul_f32_e32 v76, 0x3d372713, v72
	v_mul_f32_e32 v76, v76, v72
	v_fma_f32 v76, v76, v72, v72
	v_mul_f32_e32 v76, 0x3f4c422a, v76
	v_add_f32_e32 v76, v76, v76
	v_mul_f32_e32 v76, 0x3fb8aa3b, v76
	v_exp_f32_e32 v76, v76
	v_div_fmas_f32 v73, v73, v74, v77
	v_div_fixup_f32 v67, v73, v67, 2.0
	v_sub_f32_e32 v67, 1.0, v67
	v_add_f32_e32 v73, 1.0, v76
	v_div_scale_f32 v74, s[0:1], v73, v73, 2.0
	v_rcp_f32_e32 v76, v74
	v_add_f32_e32 v67, 1.0, v67
	v_fma_f32 v77, -v74, v76, 1.0
	v_fmac_f32_e32 v76, v77, v76
	v_div_scale_f32 v77, vcc, 2.0, v73, 2.0
	v_mul_f32_e32 v78, v77, v76
	v_fma_f32 v79, -v74, v78, v77
	v_fmac_f32_e32 v78, v79, v76
	v_fma_f32 v74, -v74, v78, v77
	v_mul_f32_e32 v77, 0x3d372713, v64
	v_mul_f32_e32 v77, v77, v64
	v_fma_f32 v77, v77, v64, v64
	v_mul_f32_e32 v77, 0x3f4c422a, v77
	v_add_f32_e32 v77, v77, v77
	v_mul_f32_e32 v77, 0x3fb8aa3b, v77
	v_exp_f32_e32 v77, v77
	v_div_fmas_f32 v74, v74, v76, v78
	v_div_fixup_f32 v73, v74, v73, 2.0
	v_mul_f32_e32 v78, 0.5, v72
	v_add_f32_e32 v74, 1.0, v77
	v_div_scale_f32 v76, s[0:1], v74, v74, 2.0
	v_rcp_f32_e32 v77, v76
	v_mul_f32_e32 v64, 0.5, v64
	v_sub_f32_e32 v73, 1.0, v73
	v_add_f32_e32 v73, 1.0, v73
	v_fma_f32 v72, -v76, v77, 1.0
	v_fmac_f32_e32 v77, v72, v77
	v_div_scale_f32 v72, vcc, 2.0, v74, 2.0
	v_mul_f32_e32 v79, v72, v77
	v_fma_f32 v80, -v76, v79, v72
	v_fmac_f32_e32 v79, v80, v77
	v_fma_f32 v72, -v76, v79, v72
	v_mul_f32_e32 v76, 0x3d372713, v70
	v_mul_f32_e32 v76, v76, v70
	v_fma_f32 v76, v76, v70, v70
	v_mul_f32_e32 v76, 0x3f4c422a, v76
	v_add_f32_e32 v76, v76, v76
	v_mul_f32_e32 v76, 0x3fb8aa3b, v76
	v_exp_f32_e32 v76, v76
	v_div_fmas_f32 v72, v72, v77, v79
	v_div_fixup_f32 v72, v72, v74, 2.0
	v_sub_f32_e32 v72, 1.0, v72
	v_add_f32_e32 v74, 1.0, v76
	v_div_scale_f32 v76, s[0:1], v74, v74, 2.0
	v_rcp_f32_e32 v77, v76
	v_add_f32_e32 v79, 1.0, v72
	v_mul_f32_e32 v70, 0.5, v70
	v_fma_f32 v72, -v76, v77, 1.0
	v_fmac_f32_e32 v77, v72, v77
	v_div_scale_f32 v72, vcc, 2.0, v74, 2.0
	v_mul_f32_e32 v80, v72, v77
	v_fma_f32 v81, -v76, v80, v72
	v_fmac_f32_e32 v80, v81, v77
	v_fma_f32 v72, -v76, v80, v72
	v_mul_f32_e32 v76, 0x3d372713, v68
	v_mul_f32_e32 v76, v76, v68
	v_fma_f32 v76, v76, v68, v68
	v_mul_f32_e32 v76, 0x3f4c422a, v76
	v_add_f32_e32 v76, v76, v76
	v_mul_f32_e32 v76, 0x3fb8aa3b, v76
	v_exp_f32_e32 v76, v76
	v_div_fmas_f32 v72, v72, v77, v80
	v_div_fixup_f32 v72, v72, v74, 2.0
	v_sub_f32_e32 v72, 1.0, v72
	v_add_f32_e32 v74, 1.0, v76
	v_div_scale_f32 v76, s[0:1], v74, v74, 2.0
	v_rcp_f32_e32 v77, v76
	v_add_f32_e32 v80, 1.0, v72
	v_mul_f32_e32 v68, 0.5, v68
	v_fma_f32 v72, -v76, v77, 1.0
	v_fmac_f32_e32 v77, v72, v77
	v_div_scale_f32 v72, vcc, 2.0, v74, 2.0
	v_mul_f32_e32 v81, v72, v77
	v_fma_f32 v82, -v76, v81, v72
	v_fmac_f32_e32 v81, v82, v77
	v_fma_f32 v72, -v76, v81, v72
	v_mul_f32_e32 v76, 0x3d372713, v75
	v_mul_f32_e32 v76, v76, v75
	v_fma_f32 v76, v76, v75, v75
	v_mul_f32_e32 v76, 0x3f4c422a, v76
	v_add_f32_e32 v76, v76, v76
	v_mul_f32_e32 v76, 0x3fb8aa3b, v76
	v_exp_f32_e32 v76, v76
	v_div_fmas_f32 v72, v72, v77, v81
	v_div_fixup_f32 v72, v72, v74, 2.0
	v_sub_f32_e32 v72, 1.0, v72
	v_add_f32_e32 v74, 1.0, v76
	v_div_scale_f32 v76, s[0:1], v74, v74, 2.0
	v_rcp_f32_e32 v77, v76
	v_add_f32_e32 v81, 1.0, v72
	v_mul_f32_e32 v75, 0.5, v75
	v_fma_f32 v72, -v76, v77, 1.0
	v_fmac_f32_e32 v77, v72, v77
	v_div_scale_f32 v72, vcc, 2.0, v74, 2.0
	v_mul_f32_e32 v82, v72, v77
	v_fma_f32 v83, -v76, v82, v72
	v_fmac_f32_e32 v82, v83, v77
	v_fma_f32 v72, -v76, v82, v72
	v_mul_f32_e32 v76, 0x3d372713, v69
	v_mul_f32_e32 v76, v76, v69
	v_fma_f32 v76, v76, v69, v69
	v_mul_f32_e32 v76, 0x3f4c422a, v76
	v_add_f32_e32 v76, v76, v76
	v_mul_f32_e32 v76, 0x3fb8aa3b, v76
	v_exp_f32_e32 v76, v76
	v_div_fmas_f32 v72, v72, v77, v82
	v_div_fixup_f32 v72, v72, v74, 2.0
	v_sub_f32_e32 v72, 1.0, v72
	v_add_f32_e32 v74, 1.0, v76
	v_div_scale_f32 v76, s[0:1], v74, v74, 2.0
	v_rcp_f32_e32 v77, v76
	v_add_f32_e32 v82, 1.0, v72
	v_mul_f32_e32 v69, 0.5, v69
	v_fma_f32 v72, -v76, v77, 1.0
	v_fmac_f32_e32 v77, v72, v77
	v_div_scale_f32 v72, vcc, 2.0, v74, 2.0
	v_mul_f32_e32 v83, v72, v77
	v_fma_f32 v84, -v76, v83, v72
	v_fmac_f32_e32 v83, v84, v77
	v_fma_f32 v72, -v76, v83, v72
	v_mul_f32_e32 v76, 0x3d372713, v71
	v_mul_f32_e32 v76, v76, v71
	v_fma_f32 v76, v76, v71, v71
	v_mul_f32_e32 v76, 0x3f4c422a, v76
	v_add_f32_e32 v76, v76, v76
	v_mul_f32_e32 v76, 0x3fb8aa3b, v76
	v_exp_f32_e32 v76, v76
	v_div_fmas_f32 v72, v72, v77, v83
	v_div_fixup_f32 v72, v72, v74, 2.0
	v_sub_f32_e32 v72, 1.0, v72
	v_add_f32_e32 v74, 1.0, v76
	v_div_scale_f32 v76, s[0:1], v74, v74, 2.0
	v_rcp_f32_e32 v77, v76
	v_add_f32_e32 v83, 1.0, v72
	v_fma_f32 v72, -v76, v77, 1.0
	v_fmac_f32_e32 v77, v72, v77
	v_div_scale_f32 v72, vcc, 2.0, v74, 2.0
	v_mul_f32_e32 v84, v72, v77
	v_fma_f32 v85, -v76, v84, v72
	v_fmac_f32_e32 v84, v85, v77
	v_fma_f32 v72, -v76, v84, v72
	v_div_fmas_f32 v72, v72, v77, v84
	v_div_fixup_f32 v72, v72, v74, 2.0
	v_mul_f32_e32 v74, 0.5, v71
	v_fma_f32 v71, v63, v67, 0
	v_fmac_f32_e32 v71, v64, v79
	v_fmac_f32_e32 v71, v68, v81
	v_fmac_f32_e32 v71, v69, v83
	v_fmac_f32_e32 v71, v78, v73
	v_sub_f32_e32 v72, 1.0, v72
	v_fmac_f32_e32 v71, v70, v80
	v_add_f32_e32 v76, 1.0, v72
	v_fmac_f32_e32 v71, v75, v82
	v_fmac_f32_e32 v71, v74, v76
	ds_bpermute_b32 v72, v144, v71
	v_xor_b32_e32 v77, 2, v190
	v_cmp_lt_i32_e32 vcc, v77, v62
	s_waitcnt lgkmcnt(0)
	v_add_f32_e32 v71, v71, v72
	v_cndmask_b32_e32 v77, v190, v77, vcc
	v_lshlrev_b32_e32 v145, 2, v77
	ds_bpermute_b32 v72, v145, v71
	v_xor_b32_e32 v77, 4, v190
	v_cmp_lt_i32_e32 vcc, v77, v62
	s_waitcnt lgkmcnt(0)
	v_add_f32_e32 v71, v71, v72
	v_cndmask_b32_e32 v77, v190, v77, vcc
	v_lshlrev_b32_e32 v146, 2, v77
	ds_bpermute_b32 v72, v146, v71
	v_xor_b32_e32 v77, 8, v190
	v_cmp_lt_i32_e32 vcc, v77, v62
	s_waitcnt lgkmcnt(0)
	v_add_f32_e32 v71, v71, v72
	v_cndmask_b32_e32 v77, v190, v77, vcc
	v_lshlrev_b32_e32 v147, 2, v77
	ds_bpermute_b32 v72, v147, v71
	v_xor_b32_e32 v77, 16, v190
	v_cmp_lt_i32_e32 vcc, v77, v62
	s_waitcnt lgkmcnt(0)
	v_add_f32_e32 v71, v71, v72
	v_cndmask_b32_e32 v77, v190, v77, vcc
	v_lshlrev_b32_e32 v148, 2, v77
	ds_bpermute_b32 v72, v148, v71
	v_xor_b32_e32 v77, 32, v190
	v_cmp_lt_i32_e32 vcc, v77, v62
	s_nop 1
	v_cndmask_b32_e32 v62, v190, v77, vcc
	v_lshlrev_b32_e32 v149, 2, v62
	s_waitcnt lgkmcnt(0)
	v_add_f32_e32 v62, v71, v72
	ds_bpermute_b32 v71, v149, v62
	s_waitcnt lgkmcnt(0)
	v_add_f32_e32 v62, v62, v71
	v_mul_f32_e32 v62, 0xbb000000, v62
	v_fma_f32 v71, v64, v79, v62
	v_fma_f32 v72, v63, v67, v62
	v_mul_f32_e32 v77, v71, v71
	v_fmac_f32_e32 v77, v72, v72
	v_fma_f32 v63, v68, v81, v62
	v_fmac_f32_e32 v77, v63, v63
	v_fma_f32 v64, v69, v83, v62
	v_fmac_f32_e32 v77, v64, v64
	v_fma_f32 v67, v78, v73, v62
	v_fmac_f32_e32 v77, v67, v67
	v_fma_f32 v69, v70, v80, v62
	v_fmac_f32_e32 v77, v69, v69
	v_fma_f32 v70, v75, v82, v62
	v_fmac_f32_e32 v77, v70, v70
	v_fmac_f32_e32 v62, v74, v76
	v_fmac_f32_e32 v77, v62, v62
	ds_bpermute_b32 v68, v144, v77
	v_lshlrev_b32_e32 v75, 3, v66
	v_and_b32_e32 v75, 0xf8, v75
	v_mad_u32_u24 v61, v75, s86, v61
	v_lshrrev_b32_e32 v86, 6, v60
	v_lshlrev_b32_e32 v87, 5, v86
	v_sub_u32_e32 v61, v61, v87
	v_lshlrev_b32_e32 v86, 1, v86
	v_and_b32_e32 v87, 15, v60
	v_xor_b32_e32 v86, v86, v87
	v_lshl_add_u32 v61, v86, 4, v61
	s_waitcnt lgkmcnt(0)
	v_add_f32_e32 v68, v77, v68
	ds_bpermute_b32 v73, v145, v68
	s_waitcnt lgkmcnt(0)
	v_add_f32_e32 v68, v68, v73
	ds_bpermute_b32 v73, v146, v68
	s_waitcnt lgkmcnt(0)
	v_add_f32_e32 v68, v68, v73
	ds_bpermute_b32 v73, v147, v68
	s_waitcnt lgkmcnt(0)
	v_add_f32_e32 v73, v68, v73
	ds_bpermute_b32 v74, v148, v73
	v_bfe_u32 v68, v66, 5, 1
	v_cmp_eq_u32_e64 s[38:39], s34, v68
	s_waitcnt lgkmcnt(0)
	v_add_f32_e32 v73, v73, v74
	ds_bpermute_b32 v74, v149, v73
	s_and_saveexec_b64 s[0:1], s[38:39]
	s_cbranch_execz .LBB0_407
	s_waitcnt lgkmcnt(0)
	v_add_f32_e32 v73, v73, v74
	v_fmamk_f32 v73, v73, 0x3b000000, v189
	v_mul_f32_e32 v74, 0x4b800000, v73
	v_cmp_gt_f32_e32 vcc, s33, v73
	s_nop 1
	v_cndmask_b32_e32 v73, v73, v74, vcc
	v_rsq_f32_e32 v73, v73
	s_nop 0
	v_mul_f32_e32 v74, 0x45800000, v73
	v_cndmask_b32_e32 v73, v73, v74, vcc
	v_mul_f32_e32 v72, v72, v73
	v_mul_f32_e32 v71, v71, v73
	v_mul_f32_e32 v63, v63, v73
	v_cvt_pk_bf16_f32 v72, v72, v65
	ds_write_b16 v61, v72
	v_cvt_pk_bf16_f32 v71, v71, v65
	ds_write_b16 v61, v71 offset:272
	v_cvt_pk_bf16_f32 v63, v63, v65
	ds_write_b16 v61, v63 offset:544
	v_mul_f32_e32 v63, v64, v73
	v_cvt_pk_bf16_f32 v63, v63, v65
	ds_write_b16 v61, v63 offset:816
	v_mul_f32_e32 v63, v67, v73
	v_cvt_pk_bf16_f32 v63, v63, v65
	ds_write_b16 v61, v63 offset:1088
	v_mul_f32_e32 v63, v69, v73
	v_cvt_pk_bf16_f32 v63, v63, v65
	ds_write_b16 v61, v63 offset:1360
	v_mul_f32_e32 v63, v70, v73
	v_mul_f32_e32 v62, v62, v73
	v_cvt_pk_bf16_f32 v63, v63, v65
	ds_write_b16 v61, v63 offset:1632
	v_cvt_pk_bf16_f32 v62, v62, v65
	ds_write_b16 v61, v62 offset:1904

.LBB0_421:
	s_or_b64 exec, exec, s[0:1]
	v_and_b32_e32 v86, 16, v61
	v_lshlrev_b32_e32 v86, 1, v86
	v_sub_u32_e32 v61, v61, v86
	v_lshlrev_b32_e32 v32, 16, v28
	v_mul_f32_e32 v33, 0x3d372713, v32
	v_mul_f32_e32 v33, v33, v32
	v_fma_f32 v33, v33, v32, v32
	v_mul_f32_e32 v33, 0x3f4c422a, v33
	v_add_f32_e32 v33, v33, v33
	v_mul_f32_e32 v33, 0x3fb8aa3b, v33
	v_exp_f32_e32 v33, v33
	v_lshlrev_b32_e32 v35, 16, v30
	v_and_b32_e32 v28, 0xffff0000, v28
	v_and_b32_e32 v30, 0xffff0000, v30
	v_add_f32_e32 v33, 1.0, v33
	v_div_scale_f32 v36, s[0:1], v33, v33, 2.0
	v_rcp_f32_e32 v37, v36
	v_lshlrev_b32_e32 v34, 16, v29
	v_lshlrev_b32_e32 v38, 16, v31
	v_and_b32_e32 v29, 0xffff0000, v29
	v_fma_f32 v39, -v36, v37, 1.0
	v_fmac_f32_e32 v37, v39, v37
	v_div_scale_f32 v39, vcc, 2.0, v33, 2.0
	v_mul_f32_e32 v40, v39, v37
	s_waitcnt lgkmcnt(0)
	v_fma_f32 v41, -v36, v40, v39
	v_fmac_f32_e32 v40, v41, v37
	v_fma_f32 v36, -v36, v40, v39
	v_mul_f32_e32 v39, 0x3d372713, v35
	v_mul_f32_e32 v39, v39, v35
	v_fma_f32 v39, v39, v35, v35
	v_mul_f32_e32 v39, 0x3f4c422a, v39
	v_add_f32_e32 v39, v39, v39
	v_mul_f32_e32 v39, 0x3fb8aa3b, v39
	v_exp_f32_e32 v39, v39
	v_div_fmas_f32 v36, v36, v37, v40
	v_div_fixup_f32 v33, v36, v33, 2.0
	v_and_b32_e32 v31, 0xffff0000, v31
	v_add_f32_e32 v36, 1.0, v39
	v_div_scale_f32 v37, s[0:1], v36, v36, 2.0
	v_rcp_f32_e32 v39, v37
	v_sub_f32_e32 v33, 1.0, v33
	v_mul_f32_e32 v32, 0.5, v32
	v_add_f32_e32 v33, 1.0, v33
	v_fma_f32 v40, -v37, v39, 1.0
	v_fmac_f32_e32 v39, v40, v39
	v_div_scale_f32 v40, vcc, 2.0, v36, 2.0
	v_mul_f32_e32 v41, v40, v39
	v_fma_f32 v42, -v37, v41, v40
	v_fmac_f32_e32 v41, v42, v39
	v_fma_f32 v37, -v37, v41, v40
	v_mul_f32_e32 v40, 0x3d372713, v28
	v_mul_f32_e32 v40, v40, v28
	v_fma_f32 v40, v40, v28, v28
	v_mul_f32_e32 v40, 0x3f4c422a, v40
	v_add_f32_e32 v40, v40, v40
	v_mul_f32_e32 v40, 0x3fb8aa3b, v40
	v_exp_f32_e32 v40, v40
	v_div_fmas_f32 v37, v37, v39, v41
	v_div_fixup_f32 v36, v37, v36, 2.0
	v_mul_f32_e32 v41, 0.5, v35
	v_add_f32_e32 v37, 1.0, v40
	v_div_scale_f32 v39, s[0:1], v37, v37, 2.0
	v_rcp_f32_e32 v40, v39
	v_sub_f32_e32 v36, 1.0, v36
	v_add_f32_e32 v36, 1.0, v36
	v_fma_f32 v35, -v39, v40, 1.0
	v_fmac_f32_e32 v40, v35, v40
	v_div_scale_f32 v35, vcc, 2.0, v37, 2.0
	v_mul_f32_e32 v42, v35, v40
	v_fma_f32 v43, -v39, v42, v35
	v_fmac_f32_e32 v42, v43, v40
	v_fma_f32 v35, -v39, v42, v35
	v_mul_f32_e32 v39, 0x3d372713, v30
	v_mul_f32_e32 v39, v39, v30
	v_fma_f32 v39, v39, v30, v30
	v_mul_f32_e32 v39, 0x3f4c422a, v39
	v_add_f32_e32 v39, v39, v39
	v_mul_f32_e32 v39, 0x3fb8aa3b, v39
	v_exp_f32_e32 v39, v39
	v_div_fmas_f32 v35, v35, v40, v42
	v_div_fixup_f32 v35, v35, v37, 2.0
	v_mul_f32_e32 v42, 0.5, v28
	v_add_f32_e32 v37, 1.0, v39
	v_div_scale_f32 v39, s[0:1], v37, v37, 2.0
	v_rcp_f32_e32 v40, v39
	v_sub_f32_e32 v35, 1.0, v35
	v_add_f32_e32 v43, 1.0, v35
	v_fma_f32 v28, -v39, v40, 1.0
	v_fmac_f32_e32 v40, v28, v40
	v_div_scale_f32 v28, vcc, 2.0, v37, 2.0
	v_mul_f32_e32 v35, v28, v40
	v_fma_f32 v44, -v39, v35, v28
	v_fmac_f32_e32 v35, v44, v40
	v_fma_f32 v28, -v39, v35, v28
	v_mul_f32_e32 v39, 0x3d372713, v34
	v_mul_f32_e32 v39, v39, v34
	v_fma_f32 v39, v39, v34, v34
	v_mul_f32_e32 v39, 0x3f4c422a, v39
	v_add_f32_e32 v39, v39, v39
	v_mul_f32_e32 v39, 0x3fb8aa3b, v39
	v_exp_f32_e32 v39, v39
	v_div_fmas_f32 v28, v28, v40, v35
	v_div_fixup_f32 v28, v28, v37, 2.0
	v_sub_f32_e32 v28, 1.0, v28
	v_add_f32_e32 v35, 1.0, v39
	v_div_scale_f32 v37, s[0:1], v35, v35, 2.0
	v_rcp_f32_e32 v39, v37
	v_add_f32_e32 v44, 1.0, v28
	v_mul_f32_e32 v40, 0.5, v30
	v_fma_f32 v28, -v37, v39, 1.0
	v_fmac_f32_e32 v39, v28, v39
	v_div_scale_f32 v28, vcc, 2.0, v35, 2.0
	v_mul_f32_e32 v30, v28, v39
	v_fma_f32 v45, -v37, v30, v28
	v_fmac_f32_e32 v30, v45, v39
	v_fma_f32 v28, -v37, v30, v28
	v_mul_f32_e32 v37, 0x3d372713, v38
	v_mul_f32_e32 v37, v37, v38
	v_fma_f32 v37, v37, v38, v38
	v_mul_f32_e32 v37, 0x3f4c422a, v37
	v_add_f32_e32 v37, v37, v37
	v_mul_f32_e32 v37, 0x3fb8aa3b, v37
	v_exp_f32_e32 v37, v37
	v_div_fmas_f32 v28, v28, v39, v30
	v_div_fixup_f32 v28, v28, v35, 2.0
	v_sub_f32_e32 v28, 1.0, v28
	v_add_f32_e32 v30, 1.0, v37
	v_div_scale_f32 v35, s[0:1], v30, v30, 2.0
	v_rcp_f32_e32 v37, v35
	v_add_f32_e32 v45, 1.0, v28
	v_mul_f32_e32 v39, 0.5, v34
	v_fma_f32 v28, -v35, v37, 1.0
	v_fmac_f32_e32 v37, v28, v37
	v_div_scale_f32 v28, vcc, 2.0, v30, 2.0
	v_mul_f32_e32 v34, v28, v37
	v_fma_f32 v46, -v35, v34, v28
	v_fmac_f32_e32 v34, v46, v37
	v_fma_f32 v28, -v35, v34, v28
	v_mul_f32_e32 v35, 0x3d372713, v29
	v_mul_f32_e32 v35, v35, v29
	v_fma_f32 v35, v35, v29, v29
	v_mul_f32_e32 v35, 0x3f4c422a, v35
	v_add_f32_e32 v35, v35, v35
	v_mul_f32_e32 v35, 0x3fb8aa3b, v35
	v_exp_f32_e32 v35, v35
	v_div_fmas_f32 v28, v28, v37, v34
	v_div_fixup_f32 v28, v28, v30, 2.0
	v_sub_f32_e32 v28, 1.0, v28
	v_add_f32_e32 v30, 1.0, v35
	v_div_scale_f32 v34, s[0:1], v30, v30, 2.0
	v_rcp_f32_e32 v35, v34
	v_mul_f32_e32 v37, 0.5, v38
	v_add_f32_e32 v38, 1.0, v28
	v_fma_f32 v28, -v34, v35, 1.0
	v_fmac_f32_e32 v35, v28, v35
	v_div_scale_f32 v28, vcc, 2.0, v30, 2.0
	v_mul_f32_e32 v46, v28, v35
	v_fma_f32 v47, -v34, v46, v28
	v_fmac_f32_e32 v46, v47, v35
	v_fma_f32 v28, -v34, v46, v28
	v_mul_f32_e32 v34, 0x3d372713, v31
	v_mul_f32_e32 v34, v34, v31
	v_fma_f32 v34, v34, v31, v31
	v_mul_f32_e32 v34, 0x3f4c422a, v34
	v_add_f32_e32 v34, v34, v34
	v_mul_f32_e32 v34, 0x3fb8aa3b, v34
	v_exp_f32_e32 v34, v34
	v_div_fmas_f32 v28, v28, v35, v46
	v_div_fixup_f32 v28, v28, v30, 2.0
	v_sub_f32_e32 v28, 1.0, v28
	v_add_f32_e32 v30, 1.0, v34
	v_div_scale_f32 v34, s[0:1], v30, v30, 2.0
	v_rcp_f32_e32 v35, v34
	v_add_f32_e32 v47, 1.0, v28
	v_mul_f32_e32 v46, 0.5, v29
	v_fma_f32 v28, -v34, v35, 1.0
	v_fmac_f32_e32 v35, v28, v35
	v_div_scale_f32 v28, vcc, 2.0, v30, 2.0
	v_mul_f32_e32 v29, v28, v35
	v_fma_f32 v48, -v34, v29, v28
	v_fmac_f32_e32 v29, v48, v35
	v_fma_f32 v28, -v34, v29, v28
	v_div_fmas_f32 v28, v28, v35, v29
	v_div_fixup_f32 v28, v28, v30, 2.0
	v_sub_f32_e32 v28, 1.0, v28
	v_add_f32_e32 v49, 1.0, v28
	v_fma_f32 v28, v32, v33, 0
	v_fmac_f32_e32 v28, v42, v43
	v_fmac_f32_e32 v28, v39, v45
	v_fmac_f32_e32 v28, v46, v47
	v_fmac_f32_e32 v28, v41, v36
	v_fmac_f32_e32 v28, v40, v44
	v_mul_f32_e32 v48, 0.5, v31
	v_fmac_f32_e32 v28, v37, v38
	v_fmac_f32_e32 v28, v48, v49
	s_nop 1
	v_add_f32_dpp v28, v28, v28 quad_perm:[1,0,3,2] row_mask:0xf bank_mask:0xf
	s_nop 1
	v_add_f32_dpp v28, v28, v28 quad_perm:[2,3,0,1] row_mask:0xf bank_mask:0xf
	s_nop 1
	v_add_f32_dpp v28, v28, v28 row_half_mirror row_mask:0xf bank_mask:0xf
	s_nop 1
	v_add_f32_dpp v28, v28, v28 row_mirror row_mask:0xf bank_mask:0xf
	s_nop 1
	v_add_f32_dpp v28, v28, v28 row_bcast:15 row_mask:0xa bank_mask:0xf
	s_nop 1
	v_add_f32_dpp v28, v28, v28 row_bcast:31 row_mask:0xc bank_mask:0xf
	s_nop 1
	v_readlane_b32 s98, v28, 63
	s_nop 1
	v_mov_b32_e32 v28, s98
	v_mul_f32_e32 v28, 0xbb000000, v28
	v_fma_f32 v34, v42, v43, v28
	v_fma_f32 v35, v32, v33, v28
	v_mul_f32_e32 v42, v34, v34
	v_fmac_f32_e32 v42, v35, v35
	v_fma_f32 v29, v39, v45, v28
	v_fmac_f32_e32 v42, v29, v29
	v_fma_f32 v30, v46, v47, v28
	v_fmac_f32_e32 v42, v30, v30
	v_fma_f32 v31, v41, v36, v28
	v_fmac_f32_e32 v42, v31, v31
	v_fma_f32 v32, v40, v44, v28
	v_fmac_f32_e32 v42, v32, v32
	v_fma_f32 v33, v37, v38, v28
	v_fmac_f32_e32 v42, v33, v33
	v_fmac_f32_e32 v28, v48, v49
	v_fmac_f32_e32 v42, v28, v28
	s_nop 1
	v_add_f32_dpp v36, v42, v42 quad_perm:[1,0,3,2] row_mask:0xf bank_mask:0xf
	s_nop 1
	v_add_f32_dpp v36, v36, v36 quad_perm:[2,3,0,1] row_mask:0xf bank_mask:0xf
	s_nop 1
	v_add_f32_dpp v36, v36, v36 row_half_mirror row_mask:0xf bank_mask:0xf
	s_nop 1
	v_add_f32_dpp v36, v36, v36 row_mirror row_mask:0xf bank_mask:0xf
	s_nop 1
	v_add_f32_dpp v36, v36, v36 row_bcast:15 row_mask:0xa bank_mask:0xf
	s_nop 1
	v_add_f32_dpp v36, v36, v36 row_bcast:31 row_mask:0xc bank_mask:0xf
	s_nop 1
	v_readlane_b32 s98, v36, 63
	s_nop 1
	v_mov_b32_e32 v36, s98
	v_mov_b32_e32 v37, 0
	s_and_saveexec_b64 s[0:1], s[38:39]
	s_cbranch_execz .LBB0_423
	s_waitcnt lgkmcnt(0)
	v_add_f32_e32 v36, v36, v37
	v_fmamk_f32 v36, v36, 0x3b000000, v189
	v_mul_f32_e32 v37, 0x4b800000, v36
	v_cmp_gt_f32_e32 vcc, s33, v36
	s_nop 1
	v_cndmask_b32_e32 v36, v36, v37, vcc
	v_rsq_f32_e32 v36, v36
	s_nop 0
	v_mul_f32_e32 v37, 0x45800000, v36
	v_cndmask_b32_e32 v36, v36, v37, vcc
	v_mul_f32_e32 v35, v35, v36
	v_mul_f32_e32 v34, v34, v36
	v_mul_f32_e32 v29, v29, v36
	v_cvt_pk_bf16_f32 v35, v35, v65
	ds_write_b16 v61, v35 offset:16
	v_cvt_pk_bf16_f32 v34, v34, v65
	ds_write_b16 v61, v34 offset:288
	v_cvt_pk_bf16_f32 v29, v29, v65
	ds_write_b16 v61, v29 offset:560
	v_mul_f32_e32 v29, v30, v36
	v_cvt_pk_bf16_f32 v29, v29, v65
	ds_write_b16 v61, v29 offset:832
	v_mul_f32_e32 v29, v31, v36
	v_cvt_pk_bf16_f32 v29, v29, v65
	ds_write_b16 v61, v29 offset:1104
	v_mul_f32_e32 v29, v32, v36
	v_cvt_pk_bf16_f32 v29, v29, v65
	ds_write_b16 v61, v29 offset:1376
	v_mul_f32_e32 v29, v33, v36
	v_mul_f32_e32 v28, v28, v36
	v_cvt_pk_bf16_f32 v29, v29, v65
	ds_write_b16 v61, v29 offset:1648
	v_cvt_pk_bf16_f32 v28, v28, v65
	ds_write_b16 v61, v28 offset:1920

.Lsgu2_issued:
	v_lshrrev_b32_e32 v222, 3, v82
	v_and_b32_e32 v223, 1, v70
	v_lshl_or_b32 v222, v223, 3, v222
	v_xor_b32_e32 v222, v222, v68
	v_lshlrev_b32_e32 v223, 4, v68
	v_sub_u32_e32 v223, v71, v223
	s_waitcnt lgkmcnt(0)
	s_barrier
	v_mov_b32_e32 v0, 0
	v_mov_b32_e32 v1, 0
	v_mov_b32_e32 v2, 0
	v_mov_b32_e32 v3, 0
	v_mov_b32_e32 v4, 0
	v_mov_b32_e32 v5, 0
	v_mov_b32_e32 v6, 0
	v_mov_b32_e32 v7, 0
	v_mov_b32_e32 v8, 0
	v_mov_b32_e32 v9, 0
	v_mov_b32_e32 v10, 0
	v_mov_b32_e32 v11, 0
	v_mov_b32_e32 v12, 0
	v_mov_b32_e32 v13, 0
	v_mov_b32_e32 v14, 0
	v_mov_b32_e32 v15, 0
	v_mov_b32_e32 v16, 0
	v_mov_b32_e32 v17, 0
	v_mov_b32_e32 v18, 0
	v_mov_b32_e32 v19, 0
	v_mov_b32_e32 v20, 0
	v_mov_b32_e32 v21, 0
	v_mov_b32_e32 v22, 0
	v_mov_b32_e32 v23, 0
	v_mov_b32_e32 v24, 0
	v_mov_b32_e32 v25, 0
	v_mov_b32_e32 v26, 0
	v_mov_b32_e32 v27, 0
	v_mov_b32_e32 v28, 0
	v_mov_b32_e32 v29, 0
	v_mov_b32_e32 v30, 0
	v_mov_b32_e32 v31, 0
	s_cmp_eq_u32 s3, 0
	s_cbranch_scc0 .Lsgu2_ph1
	v_xor_b32_e32 v248, 0, v222
	v_lshl_add_u32 v248, v248, 4, v223
	ds_read_b128 v[240:243], v248
	v_xor_b32_e32 v249, 4, v222
	v_lshl_add_u32 v249, v249, 4, v223
	ds_read_b128 v[244:247], v249 offset:8704
	s_waitcnt vmcnt(8)
	v_cmp_le_i32_e64 s[0:1], 0, v220
	v_cmp_le_i32_e64 s[2:3], 1, v220
	v_cmp_le_i32_e64 s[26:27], 2, v220
	v_cmp_le_i32_e64 s[28:29], 3, v220
	v_cndmask_b32_e64 v88, 0, v88, s[0:1]
	v_cndmask_b32_e64 v89, 0, v89, s[2:3]
	v_cndmask_b32_e64 v90, 0, v90, s[26:27]
	v_cndmask_b32_e64 v91, 0, v91, s[28:29]
	v_cmp_le_i32_e64 s[0:1], 4, v220
	v_cmp_le_i32_e64 s[2:3], 5, v220
	v_cmp_le_i32_e64 s[26:27], 6, v220
	v_cmp_le_i32_e64 s[28:29], 7, v220
	v_cndmask_b32_e64 v92, 0, v92, s[0:1]
	v_cndmask_b32_e64 v93, 0, v93, s[2:3]
	v_cndmask_b32_e64 v94, 0, v94, s[26:27]
	v_cndmask_b32_e64 v95, 0, v95, s[28:29]
	v_cmp_le_i32_e64 s[0:1], 0, v221
	v_cmp_le_i32_e64 s[2:3], 1, v221
	v_cmp_le_i32_e64 s[26:27], 2, v221
	v_cmp_le_i32_e64 s[28:29], 3, v221
	v_cndmask_b32_e64 v96, 0, v96, s[0:1]
	v_cndmask_b32_e64 v97, 0, v97, s[2:3]
	v_cndmask_b32_e64 v98, 0, v98, s[26:27]
	v_cndmask_b32_e64 v99, 0, v99, s[28:29]
	v_cmp_le_i32_e64 s[0:1], 4, v221
	v_cmp_le_i32_e64 s[2:3], 5, v221
	v_cmp_le_i32_e64 s[26:27], 6, v221
	v_cmp_le_i32_e64 s[28:29], 7, v221
	v_cndmask_b32_e64 v100, 0, v100, s[0:1]
	v_cndmask_b32_e64 v101, 0, v101, s[2:3]
	v_cndmask_b32_e64 v102, 0, v102, s[26:27]
	v_cndmask_b32_e64 v103, 0, v103, s[28:29]
	v_cvt_pk_bf16_f32 v88, v88, v89
	v_cvt_pk_bf16_f32 v89, v90, v91
	v_cvt_pk_bf16_f32 v90, v92, v93
	v_cvt_pk_bf16_f32 v91, v94, v95
	v_cvt_pk_bf16_f32 v96, v96, v97
	v_cvt_pk_bf16_f32 v97, v98, v99
	v_cvt_pk_bf16_f32 v98, v100, v101
	v_cvt_pk_bf16_f32 v99, v102, v103
	s_waitcnt lgkmcnt(0)
	v_mfma_f32_32x32x16_bf16 v[48:63], v[88:91], v[240:243], v[48:63]
	v_mfma_f32_32x32x16_bf16 v[32:47], v[88:91], v[244:247], v[32:47]
	v_xor_b32_e32 v250, 2, v222
	v_lshl_add_u32 v250, v250, 4, v223
	ds_read_b128 v[240:243], v250
	v_xor_b32_e32 v251, 6, v222
	v_lshl_add_u32 v251, v251, 4, v223
	ds_read_b128 v[244:247], v251 offset:8704
	s_waitcnt lgkmcnt(0)
	v_mfma_f32_32x32x16_bf16 v[48:63], v[96:99], v[240:243], v[48:63]
	v_mfma_f32_32x32x16_bf16 v[32:47], v[96:99], v[244:247], v[32:47]
	v_xor_b32_e32 v248, 0, v222
	v_lshl_add_u32 v248, v248, 4, v223
	ds_read_b128 v[240:243], v248
	v_xor_b32_e32 v249, 4, v222
	v_lshl_add_u32 v249, v249, 4, v223
	ds_read_b128 v[244:247], v249 offset:8704
	s_waitcnt vmcnt(4)
	v_cvt_pk_bf16_f32 v104, v104, v105
	v_cvt_pk_bf16_f32 v105, v106, v107
	v_cvt_pk_bf16_f32 v106, v108, v109
	v_cvt_pk_bf16_f32 v107, v110, v111
	v_cvt_pk_bf16_f32 v112, v112, v113
	v_cvt_pk_bf16_f32 v113, v114, v115
	v_cvt_pk_bf16_f32 v114, v116, v117
	v_cvt_pk_bf16_f32 v115, v118, v119
	s_waitcnt lgkmcnt(0)
	v_mfma_f32_32x32x16_bf16 v[16:31], v[104:107], v[240:243], v[16:31]
	v_mfma_f32_32x32x16_bf16 v[0:15], v[104:107], v[244:247], v[0:15]
	v_xor_b32_e32 v250, 2, v222
	v_lshl_add_u32 v250, v250, 4, v223
	ds_read_b128 v[240:243], v250
	v_xor_b32_e32 v251, 6, v222
	v_lshl_add_u32 v251, v251, 4, v223
	ds_read_b128 v[244:247], v251 offset:8704
	s_waitcnt lgkmcnt(0)
	v_mfma_f32_32x32x16_bf16 v[16:31], v[112:115], v[240:243], v[16:31]
	v_mfma_f32_32x32x16_bf16 v[0:15], v[112:115], v[244:247], v[0:15]
	v_xor_b32_e32 v248, 4, v222
	v_lshl_add_u32 v248, v248, 4, v223
	ds_read_b128 v[240:243], v248
	v_xor_b32_e32 v249, 0, v222
	v_lshl_add_u32 v249, v249, 4, v223
	ds_read_b128 v[244:247], v249 offset:8704
	s_waitcnt vmcnt(0)
	v_cmp_le_i32_e64 s[0:1], 0, v220
	v_cmp_le_i32_e64 s[2:3], 1, v220
	v_cmp_le_i32_e64 s[26:27], 2, v220
	v_cmp_le_i32_e64 s[28:29], 3, v220
	v_cndmask_b32_e64 v120, 0, v120, s[0:1]
	v_cndmask_b32_e64 v121, 0, v121, s[2:3]
	v_cndmask_b32_e64 v122, 0, v122, s[26:27]
	v_cndmask_b32_e64 v123, 0, v123, s[28:29]
	v_cmp_le_i32_e64 s[0:1], 4, v220
	v_cmp_le_i32_e64 s[2:3], 5, v220
	v_cmp_le_i32_e64 s[26:27], 6, v220
	v_cmp_le_i32_e64 s[28:29], 7, v220
	v_cndmask_b32_e64 v124, 0, v124, s[0:1]
	v_cndmask_b32_e64 v125, 0, v125, s[2:3]
	v_cndmask_b32_e64 v126, 0, v126, s[26:27]
	v_cndmask_b32_e64 v127, 0, v127, s[28:29]
	v_cmp_le_i32_e64 s[0:1], 0, v221
	v_cmp_le_i32_e64 s[2:3], 1, v221
	v_cmp_le_i32_e64 s[26:27], 2, v221
	v_cmp_le_i32_e64 s[28:29], 3, v221
	v_cndmask_b32_e64 v128, 0, v128, s[0:1]
	v_cndmask_b32_e64 v129, 0, v129, s[2:3]
	v_cndmask_b32_e64 v130, 0, v130, s[26:27]
	v_cndmask_b32_e64 v131, 0, v131, s[28:29]
	v_cmp_le_i32_e64 s[0:1], 4, v221
	v_cmp_le_i32_e64 s[2:3], 5, v221
	v_cmp_le_i32_e64 s[26:27], 6, v221
	v_cmp_le_i32_e64 s[28:29], 7, v221
	v_cndmask_b32_e64 v132, 0, v132, s[0:1]
	v_cndmask_b32_e64 v133, 0, v133, s[2:3]
	v_cndmask_b32_e64 v134, 0, v134, s[26:27]
	v_cndmask_b32_e64 v135, 0, v135, s[28:29]
	v_cvt_pk_bf16_f32 v120, v120, v121
	v_cvt_pk_bf16_f32 v121, v122, v123
	v_cvt_pk_bf16_f32 v122, v124, v125
	v_cvt_pk_bf16_f32 v123, v126, v127
	v_cvt_pk_bf16_f32 v128, v128, v129
	v_cvt_pk_bf16_f32 v129, v130, v131
	v_cvt_pk_bf16_f32 v130, v132, v133
	v_cvt_pk_bf16_f32 v131, v134, v135
	s_waitcnt lgkmcnt(0)
	v_mfma_f32_32x32x16_bf16 v[16:31], v[120:123], v[240:243], v[16:31]
	v_mfma_f32_32x32x16_bf16 v[0:15], v[120:123], v[244:247], v[0:15]
	v_xor_b32_e32 v250, 6, v222
	v_lshl_add_u32 v250, v250, 4, v223
	ds_read_b128 v[240:243], v250
	v_xor_b32_e32 v251, 2, v222
	v_lshl_add_u32 v251, v251, 4, v223
	ds_read_b128 v[244:247], v251 offset:8704
	s_waitcnt lgkmcnt(0)
	v_mfma_f32_32x32x16_bf16 v[16:31], v[128:131], v[240:243], v[16:31]
	v_mfma_f32_32x32x16_bf16 v[0:15], v[128:131], v[244:247], v[0:15]
	s_branch .LBB0_404
.Lsgu2_ph1:
	v_xor_b32_e32 v248, 0, v222
	v_lshl_add_u32 v248, v248, 4, v223
	ds_read_b128 v[240:243], v248
	v_xor_b32_e32 v249, 4, v222
	v_lshl_add_u32 v249, v249, 4, v223
	ds_read_b128 v[244:247], v249 offset:8704
	s_waitcnt vmcnt(20)
	v_cvt_pk_bf16_f32 v88, v88, v89
	v_cvt_pk_bf16_f32 v89, v90, v91
	v_cvt_pk_bf16_f32 v90, v92, v93
	v_cvt_pk_bf16_f32 v91, v94, v95
	v_cvt_pk_bf16_f32 v96, v96, v97
	v_cvt_pk_bf16_f32 v97, v98, v99
	v_cvt_pk_bf16_f32 v98, v100, v101
	v_cvt_pk_bf16_f32 v99, v102, v103
	s_waitcnt lgkmcnt(0)
	v_mfma_f32_32x32x16_bf16 v[48:63], v[88:91], v[240:243], v[48:63]
	v_mfma_f32_32x32x16_bf16 v[32:47], v[88:91], v[244:247], v[32:47]
	v_xor_b32_e32 v250, 2, v222
	v_lshl_add_u32 v250, v250, 4, v223
	ds_read_b128 v[240:243], v250
	v_xor_b32_e32 v251, 6, v222
	v_lshl_add_u32 v251, v251, 4, v223
	ds_read_b128 v[244:247], v251 offset:8704
	s_waitcnt lgkmcnt(0)
	v_mfma_f32_32x32x16_bf16 v[48:63], v[96:99], v[240:243], v[48:63]
	v_mfma_f32_32x32x16_bf16 v[32:47], v[96:99], v[244:247], v[32:47]
	global_load_dwordx4 v[88:91], v[218:219], off offset:320
	global_load_dwordx4 v[92:95], v[218:219], off offset:336
	global_load_dwordx4 v[96:99], v[218:219], off offset:384
	global_load_dwordx4 v[100:103], v[218:219], off offset:400
	v_xor_b32_e32 v248, 4, v222
	v_lshl_add_u32 v248, v248, 4, v223
	ds_read_b128 v[240:243], v248
	v_xor_b32_e32 v249, 0, v222
	v_lshl_add_u32 v249, v249, 4, v223
	ds_read_b128 v[244:247], v249 offset:8704
	s_waitcnt vmcnt(20)
	v_cvt_pk_bf16_f32 v104, v104, v105
	v_cvt_pk_bf16_f32 v105, v106, v107
	v_cvt_pk_bf16_f32 v106, v108, v109
	v_cvt_pk_bf16_f32 v107, v110, v111
	v_cvt_pk_bf16_f32 v112, v112, v113
	v_cvt_pk_bf16_f32 v113, v114, v115
	v_cvt_pk_bf16_f32 v114, v116, v117
	v_cvt_pk_bf16_f32 v115, v118, v119
	s_waitcnt lgkmcnt(0)
	v_mfma_f32_32x32x16_bf16 v[48:63], v[104:107], v[240:243], v[48:63]
	v_mfma_f32_32x32x16_bf16 v[32:47], v[104:107], v[244:247], v[32:47]
	v_xor_b32_e32 v250, 6, v222
	v_lshl_add_u32 v250, v250, 4, v223
	ds_read_b128 v[240:243], v250
	v_xor_b32_e32 v251, 2, v222
	v_lshl_add_u32 v251, v251, 4, v223
	ds_read_b128 v[244:247], v251 offset:8704
	s_waitcnt lgkmcnt(0)
	v_mfma_f32_32x32x16_bf16 v[48:63], v[112:115], v[240:243], v[48:63]
	v_mfma_f32_32x32x16_bf16 v[32:47], v[112:115], v[244:247], v[32:47]
	v_xor_b32_e32 v248, 8, v222
	v_lshl_add_u32 v248, v248, 4, v223
	ds_read_b128 v[240:243], v248
	v_xor_b32_e32 v249, 12, v222
	v_lshl_add_u32 v249, v249, 4, v223
	ds_read_b128 v[244:247], v249 offset:8704
	s_waitcnt vmcnt(16)
	v_cmp_le_i32_e64 s[0:1], 0, v220
	v_cmp_le_i32_e64 s[2:3], 1, v220
	v_cmp_le_i32_e64 s[26:27], 2, v220
	v_cmp_le_i32_e64 s[28:29], 3, v220
	v_cndmask_b32_e64 v120, 0, v120, s[0:1]
	v_cndmask_b32_e64 v121, 0, v121, s[2:3]
	v_cndmask_b32_e64 v122, 0, v122, s[26:27]
	v_cndmask_b32_e64 v123, 0, v123, s[28:29]
	v_cmp_le_i32_e64 s[0:1], 4, v220
	v_cmp_le_i32_e64 s[2:3], 5, v220
	v_cmp_le_i32_e64 s[26:27], 6, v220
	v_cmp_le_i32_e64 s[28:29], 7, v220
	v_cndmask_b32_e64 v124, 0, v124, s[0:1]
	v_cndmask_b32_e64 v125, 0, v125, s[2:3]
	v_cndmask_b32_e64 v126, 0, v126, s[26:27]
	v_cndmask_b32_e64 v127, 0, v127, s[28:29]
	v_cmp_le_i32_e64 s[0:1], 0, v221
	v_cmp_le_i32_e64 s[2:3], 1, v221
	v_cmp_le_i32_e64 s[26:27], 2, v221
	v_cmp_le_i32_e64 s[28:29], 3, v221
	v_cndmask_b32_e64 v128, 0, v128, s[0:1]
	v_cndmask_b32_e64 v129, 0, v129, s[2:3]
	v_cndmask_b32_e64 v130, 0, v130, s[26:27]
	v_cndmask_b32_e64 v131, 0, v131, s[28:29]
	v_cmp_le_i32_e64 s[0:1], 4, v221
	v_cmp_le_i32_e64 s[2:3], 5, v221
	v_cmp_le_i32_e64 s[26:27], 6, v221
	v_cmp_le_i32_e64 s[28:29], 7, v221
	v_cndmask_b32_e64 v132, 0, v132, s[0:1]
	v_cndmask_b32_e64 v133, 0, v133, s[2:3]
	v_cndmask_b32_e64 v134, 0, v134, s[26:27]
	v_cndmask_b32_e64 v135, 0, v135, s[28:29]
	v_cvt_pk_bf16_f32 v120, v120, v121
	v_cvt_pk_bf16_f32 v121, v122, v123
	v_cvt_pk_bf16_f32 v122, v124, v125
	v_cvt_pk_bf16_f32 v123, v126, v127
	v_cvt_pk_bf16_f32 v128, v128, v129
	v_cvt_pk_bf16_f32 v129, v130, v131
	v_cvt_pk_bf16_f32 v130, v132, v133
	v_cvt_pk_bf16_f32 v131, v134, v135
	s_waitcnt lgkmcnt(0)
	v_mfma_f32_32x32x16_bf16 v[48:63], v[120:123], v[240:243], v[48:63]
	v_mfma_f32_32x32x16_bf16 v[32:47], v[120:123], v[244:247], v[32:47]
	v_xor_b32_e32 v250, 10, v222
	v_lshl_add_u32 v250, v250, 4, v223
	ds_read_b128 v[240:243], v250
	v_xor_b32_e32 v251, 14, v222
	v_lshl_add_u32 v251, v251, 4, v223
	ds_read_b128 v[244:247], v251 offset:8704
	s_waitcnt lgkmcnt(0)
	v_mfma_f32_32x32x16_bf16 v[48:63], v[128:131], v[240:243], v[48:63]
	v_mfma_f32_32x32x16_bf16 v[32:47], v[128:131], v[244:247], v[32:47]
	v_xor_b32_e32 v248, 0, v222
	v_lshl_add_u32 v248, v248, 4, v223
	ds_read_b128 v[240:243], v248
	v_xor_b32_e32 v249, 4, v222
	v_lshl_add_u32 v249, v249, 4, v223
	ds_read_b128 v[244:247], v249 offset:8704
	s_waitcnt vmcnt(12)
	v_cvt_pk_bf16_f32 v136, v136, v137
	v_cvt_pk_bf16_f32 v137, v138, v139
	v_cvt_pk_bf16_f32 v138, v140, v141
	v_cvt_pk_bf16_f32 v139, v142, v143
	v_cvt_pk_bf16_f32 v152, v152, v153
	v_cvt_pk_bf16_f32 v153, v154, v155
	v_cvt_pk_bf16_f32 v154, v156, v157
	v_cvt_pk_bf16_f32 v155, v158, v159
	s_waitcnt lgkmcnt(0)
	v_mfma_f32_32x32x16_bf16 v[16:31], v[136:139], v[240:243], v[16:31]
	v_mfma_f32_32x32x16_bf16 v[0:15], v[136:139], v[244:247], v[0:15]
	v_xor_b32_e32 v250, 2, v222
	v_lshl_add_u32 v250, v250, 4, v223
	ds_read_b128 v[240:243], v250
	v_xor_b32_e32 v251, 6, v222
	v_lshl_add_u32 v251, v251, 4, v223
	ds_read_b128 v[244:247], v251 offset:8704
	s_waitcnt lgkmcnt(0)
	v_mfma_f32_32x32x16_bf16 v[16:31], v[152:155], v[240:243], v[16:31]
	v_mfma_f32_32x32x16_bf16 v[0:15], v[152:155], v[244:247], v[0:15]
	v_xor_b32_e32 v248, 4, v222
	v_lshl_add_u32 v248, v248, 4, v223
	ds_read_b128 v[240:243], v248
	v_xor_b32_e32 v249, 0, v222
	v_lshl_add_u32 v249, v249, 4, v223
	ds_read_b128 v[244:247], v249 offset:8704
	s_waitcnt vmcnt(8)
	v_cvt_pk_bf16_f32 v200, v200, v201
	v_cvt_pk_bf16_f32 v201, v202, v203
	v_cvt_pk_bf16_f32 v202, v204, v205
	v_cvt_pk_bf16_f32 v203, v206, v207
	v_cvt_pk_bf16_f32 v208, v208, v209
	v_cvt_pk_bf16_f32 v209, v210, v211
	v_cvt_pk_bf16_f32 v210, v212, v213
	v_cvt_pk_bf16_f32 v211, v214, v215
	s_waitcnt lgkmcnt(0)
	v_mfma_f32_32x32x16_bf16 v[16:31], v[200:203], v[240:243], v[16:31]
	v_mfma_f32_32x32x16_bf16 v[0:15], v[200:203], v[244:247], v[0:15]
	v_xor_b32_e32 v250, 6, v222
	v_lshl_add_u32 v250, v250, 4, v223
	ds_read_b128 v[240:243], v250
	v_xor_b32_e32 v251, 2, v222
	v_lshl_add_u32 v251, v251, 4, v223
	ds_read_b128 v[244:247], v251 offset:8704
	s_waitcnt lgkmcnt(0)
	v_mfma_f32_32x32x16_bf16 v[16:31], v[208:211], v[240:243], v[16:31]
	v_mfma_f32_32x32x16_bf16 v[0:15], v[208:211], v[244:247], v[0:15]
	v_xor_b32_e32 v248, 8, v222
	v_lshl_add_u32 v248, v248, 4, v223
	ds_read_b128 v[240:243], v248
	v_xor_b32_e32 v249, 12, v222
	v_lshl_add_u32 v249, v249, 4, v223
	ds_read_b128 v[244:247], v249 offset:8704
	s_waitcnt vmcnt(4)
	v_cvt_pk_bf16_f32 v224, v224, v225
	v_cvt_pk_bf16_f32 v225, v226, v227
	v_cvt_pk_bf16_f32 v226, v228, v229
	v_cvt_pk_bf16_f32 v227, v230, v231
	v_cvt_pk_bf16_f32 v232, v232, v233
	v_cvt_pk_bf16_f32 v233, v234, v235
	v_cvt_pk_bf16_f32 v234, v236, v237
	v_cvt_pk_bf16_f32 v235, v238, v239
	s_waitcnt lgkmcnt(0)
	v_mfma_f32_32x32x16_bf16 v[16:31], v[224:227], v[240:243], v[16:31]
	v_mfma_f32_32x32x16_bf16 v[0:15], v[224:227], v[244:247], v[0:15]
	v_xor_b32_e32 v250, 10, v222
	v_lshl_add_u32 v250, v250, 4, v223
	ds_read_b128 v[240:243], v250
	v_xor_b32_e32 v251, 14, v222
	v_lshl_add_u32 v251, v251, 4, v223
	ds_read_b128 v[244:247], v251 offset:8704
	s_waitcnt lgkmcnt(0)
	v_mfma_f32_32x32x16_bf16 v[16:31], v[232:235], v[240:243], v[16:31]
	v_mfma_f32_32x32x16_bf16 v[0:15], v[232:235], v[244:247], v[0:15]
	v_xor_b32_e32 v248, 12, v222
	v_lshl_add_u32 v248, v248, 4, v223
	ds_read_b128 v[240:243], v248
	v_xor_b32_e32 v249, 8, v222
	v_lshl_add_u32 v249, v249, 4, v223
	ds_read_b128 v[244:247], v249 offset:8704
	s_waitcnt vmcnt(0)
	v_cmp_le_i32_e64 s[0:1], 0, v220
	v_cmp_le_i32_e64 s[2:3], 1, v220
	v_cmp_le_i32_e64 s[26:27], 2, v220
	v_cmp_le_i32_e64 s[28:29], 3, v220
	v_cndmask_b32_e64 v88, 0, v88, s[0:1]
	v_cndmask_b32_e64 v89, 0, v89, s[2:3]
	v_cndmask_b32_e64 v90, 0, v90, s[26:27]
	v_cndmask_b32_e64 v91, 0, v91, s[28:29]
	v_cmp_le_i32_e64 s[0:1], 4, v220
	v_cmp_le_i32_e64 s[2:3], 5, v220
	v_cmp_le_i32_e64 s[26:27], 6, v220
	v_cmp_le_i32_e64 s[28:29], 7, v220
	v_cndmask_b32_e64 v92, 0, v92, s[0:1]
	v_cndmask_b32_e64 v93, 0, v93, s[2:3]
	v_cndmask_b32_e64 v94, 0, v94, s[26:27]
	v_cndmask_b32_e64 v95, 0, v95, s[28:29]
	v_cmp_le_i32_e64 s[0:1], 0, v221
	v_cmp_le_i32_e64 s[2:3], 1, v221
	v_cmp_le_i32_e64 s[26:27], 2, v221
	v_cmp_le_i32_e64 s[28:29], 3, v221
	v_cndmask_b32_e64 v96, 0, v96, s[0:1]
	v_cndmask_b32_e64 v97, 0, v97, s[2:3]
	v_cndmask_b32_e64 v98, 0, v98, s[26:27]
	v_cndmask_b32_e64 v99, 0, v99, s[28:29]
	v_cmp_le_i32_e64 s[0:1], 4, v221
	v_cmp_le_i32_e64 s[2:3], 5, v221
	v_cmp_le_i32_e64 s[26:27], 6, v221
	v_cmp_le_i32_e64 s[28:29], 7, v221
	v_cndmask_b32_e64 v100, 0, v100, s[0:1]
	v_cndmask_b32_e64 v101, 0, v101, s[2:3]
	v_cndmask_b32_e64 v102, 0, v102, s[26:27]
	v_cndmask_b32_e64 v103, 0, v103, s[28:29]
	v_cvt_pk_bf16_f32 v88, v88, v89
	v_cvt_pk_bf16_f32 v89, v90, v91
	v_cvt_pk_bf16_f32 v90, v92, v93
	v_cvt_pk_bf16_f32 v91, v94, v95
	v_cvt_pk_bf16_f32 v96, v96, v97
	v_cvt_pk_bf16_f32 v97, v98, v99
	v_cvt_pk_bf16_f32 v98, v100, v101
	v_cvt_pk_bf16_f32 v99, v102, v103
	s_waitcnt lgkmcnt(0)
	v_mfma_f32_32x32x16_bf16 v[16:31], v[88:91], v[240:243], v[16:31]
	v_mfma_f32_32x32x16_bf16 v[0:15], v[88:91], v[244:247], v[0:15]
	v_xor_b32_e32 v250, 14, v222
	v_lshl_add_u32 v250, v250, 4, v223
	ds_read_b128 v[240:243], v250
	v_xor_b32_e32 v251, 10, v222
	v_lshl_add_u32 v251, v251, 4, v223
	ds_read_b128 v[244:247], v251 offset:8704
	s_waitcnt lgkmcnt(0)
	v_mfma_f32_32x32x16_bf16 v[16:31], v[96:99], v[240:243], v[16:31]
	v_mfma_f32_32x32x16_bf16 v[0:15], v[96:99], v[244:247], v[0:15]
	s_branch .LBB0_404
